# top-k candidate scan enters at 8-candidate granularity (skips more provably-future blocks), on top of v33
# baseline (speedup 1.0000x reference)
; __device__ __forceinline__ void nsa_tile(const Params& p, int qb, int bg, char* smem) {
;     ...
;             const bool forced = (lane == 0) || (lane == cur) || (lane == cur - 1);
;             const bool future = lane > cur;
;             v = forced ? 1e9f : (future ? -1e9f : v);
;             int cnt = 0;
; #pragma unroll
;             for (int i = 0; i < 64; ++i) {
;                 const float vi = __uint_as_float(__builtin_amdgcn_readlane(__float_as_uint(v), i));
;                 cnt += ((vi > v) || (vi == v && i < lane)) ? 1 : 0;
;             }
.LBB0_357:
	v_ashrrev_i32_e32 v56, 6, v55
	v_cmp_lt_i32_e32 vcc, 15, v56
	s_mov_b64 s[2:3], 0
	s_and_saveexec_b64 s[42:43], vcc
	s_xor_b64 s[44:45], exec, s[42:43]
	s_cbranch_execz .LBB0_360
	ds_read2st64_b32 v[52:53], v54 offset1:32
	ds_read2st64_b32 v[58:59], v54 offset0:64 offset1:96
	v_readlane_b32 s2, v244, 19
	v_readlane_b32 s3, v244, 20
	v_cmp_eq_u32_e32 vcc, v78, v56
	s_waitcnt lgkmcnt(1)
	v_mov_b32_e32 v60, v52
	s_waitcnt lgkmcnt(0)
	v_mov_b32_e32 v61, v58
	v_mov_b32_e32 v58, v53
	v_pk_add_f32 v[52:53], v[60:61], v[58:59]
	v_cmp_le_i32_e64 s[42:43], v78, v56
	v_add_f32_e32 v52, v52, v53
	v_add_u32_e32 v53, -1, v56
	v_cndmask_b32_e64 v52, 0, v52, s[2:3]
	s_or_b64 s[2:3], s[4:5], vcc
	v_cmp_eq_u32_e32 vcc, v78, v53
	s_or_b64 vcc, s[2:3], vcc
	v_cndmask_b32_e64 v52, v109, v52, s[42:43]
	v_cndmask_b32_e32 v52, v52, v110, vcc
	v_readfirstlane_b32 s46, v56
	v_ashrrev_i32_e32 v53, 31, v52
	v_or_b32_e32 v53, 0x80000000, v53
	v_xor_b32_e32 v247, v52, v53
	v_sub_u32_e32 v246, 63, v78
	v_mov_b32_e32 v52, 0
	s_cmp_lt_u32 s46, 24
	s_cbranch_scc1 .Ltk_c23
	s_cmp_lt_u32 s46, 32
	s_cbranch_scc1 .Ltk_c31
	s_cmp_lt_u32 s46, 40
	s_cbranch_scc1 .Ltk_c39
	s_cmp_lt_u32 s46, 48
	s_cbranch_scc1 .Ltk_c47
	s_cmp_lt_u32 s46, 56
	s_cbranch_scc1 .Ltk_c55
	v_readlane_b32 s3, v247, 63
	v_readlane_b32 s47, v247, 62
	s_movk_i32 s2, 0
	s_movk_i32 s46, 1
	v_cmp_gt_u64_e32 vcc, s[2:3], v[246:247]
	v_cmp_gt_u64_e64 s[98:99], s[46:47], v[246:247]
	v_readlane_b32 s3, v247, 61
	v_readlane_b32 s47, v247, 60
	v_addc_co_u32_e32 v52, vcc, 0, v52, vcc
	v_addc_co_u32_e64 v52, s[100:101], 0, v52, s[98:99]
	s_movk_i32 s2, 2
	s_movk_i32 s46, 3
	v_cmp_gt_u64_e32 vcc, s[2:3], v[246:247]
	v_cmp_gt_u64_e64 s[98:99], s[46:47], v[246:247]
	v_readlane_b32 s3, v247, 59
	v_readlane_b32 s47, v247, 58
	v_addc_co_u32_e32 v52, vcc, 0, v52, vcc
	v_addc_co_u32_e64 v52, s[100:101], 0, v52, s[98:99]
	s_movk_i32 s2, 4
	s_movk_i32 s46, 5
	v_cmp_gt_u64_e32 vcc, s[2:3], v[246:247]
	v_cmp_gt_u64_e64 s[98:99], s[46:47], v[246:247]
	v_readlane_b32 s3, v247, 57
	v_readlane_b32 s47, v247, 56
	v_addc_co_u32_e32 v52, vcc, 0, v52, vcc
	v_addc_co_u32_e64 v52, s[100:101], 0, v52, s[98:99]
	s_movk_i32 s2, 6
	s_movk_i32 s46, 7
	v_cmp_gt_u64_e32 vcc, s[2:3], v[246:247]
	v_cmp_gt_u64_e64 s[98:99], s[46:47], v[246:247]
	s_nop 1
	v_addc_co_u32_e32 v52, vcc, 0, v52, vcc
	v_addc_co_u32_e64 v52, s[100:101], 0, v52, s[98:99]
.Ltk_c55:
	v_readlane_b32 s3, v247, 55
	v_readlane_b32 s47, v247, 54
	s_movk_i32 s2, 8
	s_movk_i32 s46, 9
	v_cmp_gt_u64_e32 vcc, s[2:3], v[246:247]
	v_cmp_gt_u64_e64 s[98:99], s[46:47], v[246:247]
	v_readlane_b32 s3, v247, 53
	v_readlane_b32 s47, v247, 52
	v_addc_co_u32_e32 v52, vcc, 0, v52, vcc
	v_addc_co_u32_e64 v52, s[100:101], 0, v52, s[98:99]
	s_movk_i32 s2, 10
	s_movk_i32 s46, 11
	v_cmp_gt_u64_e32 vcc, s[2:3], v[246:247]
	v_cmp_gt_u64_e64 s[98:99], s[46:47], v[246:247]
	v_readlane_b32 s3, v247, 51
	v_readlane_b32 s47, v247, 50
	v_addc_co_u32_e32 v52, vcc, 0, v52, vcc
	v_addc_co_u32_e64 v52, s[100:101], 0, v52, s[98:99]
	s_movk_i32 s2, 12
	s_movk_i32 s46, 13
	v_cmp_gt_u64_e32 vcc, s[2:3], v[246:247]
	v_cmp_gt_u64_e64 s[98:99], s[46:47], v[246:247]
	v_readlane_b32 s3, v247, 49
	v_readlane_b32 s47, v247, 48
	v_addc_co_u32_e32 v52, vcc, 0, v52, vcc
	v_addc_co_u32_e64 v52, s[100:101], 0, v52, s[98:99]
	s_movk_i32 s2, 14
	s_movk_i32 s46, 15
	v_cmp_gt_u64_e32 vcc, s[2:3], v[246:247]
	v_cmp_gt_u64_e64 s[98:99], s[46:47], v[246:247]
	s_nop 1
	v_addc_co_u32_e32 v52, vcc, 0, v52, vcc
	v_addc_co_u32_e64 v52, s[100:101], 0, v52, s[98:99]
.Ltk_c47:
	v_readlane_b32 s3, v247, 47
	v_readlane_b32 s47, v247, 46
	s_movk_i32 s2, 16
	s_movk_i32 s46, 17
	v_cmp_gt_u64_e32 vcc, s[2:3], v[246:247]
	v_cmp_gt_u64_e64 s[98:99], s[46:47], v[246:247]
	v_readlane_b32 s3, v247, 45
	v_readlane_b32 s47, v247, 44
	v_addc_co_u32_e32 v52, vcc, 0, v52, vcc
	v_addc_co_u32_e64 v52, s[100:101], 0, v52, s[98:99]
	s_movk_i32 s2, 18
	s_movk_i32 s46, 19
	v_cmp_gt_u64_e32 vcc, s[2:3], v[246:247]
	v_cmp_gt_u64_e64 s[98:99], s[46:47], v[246:247]
	v_readlane_b32 s3, v247, 43
	v_readlane_b32 s47, v247, 42
	v_addc_co_u32_e32 v52, vcc, 0, v52, vcc
	v_addc_co_u32_e64 v52, s[100:101], 0, v52, s[98:99]
	s_movk_i32 s2, 20
	s_movk_i32 s46, 21
	v_cmp_gt_u64_e32 vcc, s[2:3], v[246:247]
	v_cmp_gt_u64_e64 s[98:99], s[46:47], v[246:247]
	v_readlane_b32 s3, v247, 41
	v_readlane_b32 s47, v247, 40
	v_addc_co_u32_e32 v52, vcc, 0, v52, vcc
	v_addc_co_u32_e64 v52, s[100:101], 0, v52, s[98:99]
	s_movk_i32 s2, 22
	s_movk_i32 s46, 23
	v_cmp_gt_u64_e32 vcc, s[2:3], v[246:247]
	v_cmp_gt_u64_e64 s[98:99], s[46:47], v[246:247]
	s_nop 1
	v_addc_co_u32_e32 v52, vcc, 0, v52, vcc
	v_addc_co_u32_e64 v52, s[100:101], 0, v52, s[98:99]
.Ltk_c39:
	v_readlane_b32 s3, v247, 39
	v_readlane_b32 s47, v247, 38
	s_movk_i32 s2, 24
	s_movk_i32 s46, 25
	v_cmp_gt_u64_e32 vcc, s[2:3], v[246:247]
	v_cmp_gt_u64_e64 s[98:99], s[46:47], v[246:247]
	v_readlane_b32 s3, v247, 37
	v_readlane_b32 s47, v247, 36
	v_addc_co_u32_e32 v52, vcc, 0, v52, vcc
	v_addc_co_u32_e64 v52, s[100:101], 0, v52, s[98:99]
	s_movk_i32 s2, 26
	s_movk_i32 s46, 27
	v_cmp_gt_u64_e32 vcc, s[2:3], v[246:247]
	v_cmp_gt_u64_e64 s[98:99], s[46:47], v[246:247]
	v_readlane_b32 s3, v247, 35
	v_readlane_b32 s47, v247, 34
	v_addc_co_u32_e32 v52, vcc, 0, v52, vcc
	v_addc_co_u32_e64 v52, s[100:101], 0, v52, s[98:99]
	s_movk_i32 s2, 28
	s_movk_i32 s46, 29
	v_cmp_gt_u64_e32 vcc, s[2:3], v[246:247]
	v_cmp_gt_u64_e64 s[98:99], s[46:47], v[246:247]
	v_readlane_b32 s3, v247, 33
	v_readlane_b32 s47, v247, 32
	v_addc_co_u32_e32 v52, vcc, 0, v52, vcc
	v_addc_co_u32_e64 v52, s[100:101], 0, v52, s[98:99]
	s_movk_i32 s2, 30
	s_movk_i32 s46, 31
	v_cmp_gt_u64_e32 vcc, s[2:3], v[246:247]
	v_cmp_gt_u64_e64 s[98:99], s[46:47], v[246:247]
	s_nop 1
	v_addc_co_u32_e32 v52, vcc, 0, v52, vcc
	v_addc_co_u32_e64 v52, s[100:101], 0, v52, s[98:99]
; __device__ __forceinline__ void nsa_tile(const Params& p, int qb, int bg, char* smem) {
;     ...
;             int cnt = 0;
; #pragma unroll
;             for (int i = 0; i < 64; ++i) {
;                 const float vi = __uint_as_float(__builtin_amdgcn_readlane(__float_as_uint(v), i));
;                 cnt += ((vi > v) || (vi == v && i < lane)) ? 1 : 0;
;             }
;             const u64 mk = __ballot((cnt < 16) && !future);
;             if (lane == 0) selmask[tok] = mk;
.Ltk_c31:
	v_readlane_b32 s3, v247, 31
	v_readlane_b32 s47, v247, 30
	s_movk_i32 s2, 32
	s_movk_i32 s46, 33
	v_cmp_gt_u64_e32 vcc, s[2:3], v[246:247]
	v_cmp_gt_u64_e64 s[98:99], s[46:47], v[246:247]
	v_readlane_b32 s3, v247, 29
	v_readlane_b32 s47, v247, 28
	v_addc_co_u32_e32 v52, vcc, 0, v52, vcc
	v_addc_co_u32_e64 v52, s[100:101], 0, v52, s[98:99]
	s_movk_i32 s2, 34
	s_movk_i32 s46, 35
	v_cmp_gt_u64_e32 vcc, s[2:3], v[246:247]
	v_cmp_gt_u64_e64 s[98:99], s[46:47], v[246:247]
	v_readlane_b32 s3, v247, 27
	v_readlane_b32 s47, v247, 26
	v_addc_co_u32_e32 v52, vcc, 0, v52, vcc
	v_addc_co_u32_e64 v52, s[100:101], 0, v52, s[98:99]
	s_movk_i32 s2, 36
	s_movk_i32 s46, 37
	v_cmp_gt_u64_e32 vcc, s[2:3], v[246:247]
	v_cmp_gt_u64_e64 s[98:99], s[46:47], v[246:247]
	v_readlane_b32 s3, v247, 25
	v_readlane_b32 s47, v247, 24
	v_addc_co_u32_e32 v52, vcc, 0, v52, vcc
	v_addc_co_u32_e64 v52, s[100:101], 0, v52, s[98:99]
	s_movk_i32 s2, 38
	s_movk_i32 s46, 39
	v_cmp_gt_u64_e32 vcc, s[2:3], v[246:247]
	v_cmp_gt_u64_e64 s[98:99], s[46:47], v[246:247]
	s_nop 1
	v_addc_co_u32_e32 v52, vcc, 0, v52, vcc
	v_addc_co_u32_e64 v52, s[100:101], 0, v52, s[98:99]
.Ltk_c23:
	v_readlane_b32 s3, v247, 23
	v_readlane_b32 s47, v247, 22
	s_movk_i32 s2, 40
	s_movk_i32 s46, 41
	v_cmp_gt_u64_e32 vcc, s[2:3], v[246:247]
	v_cmp_gt_u64_e64 s[98:99], s[46:47], v[246:247]
	v_readlane_b32 s3, v247, 21
	v_readlane_b32 s47, v247, 20
	v_addc_co_u32_e32 v52, vcc, 0, v52, vcc
	v_addc_co_u32_e64 v52, s[100:101], 0, v52, s[98:99]
	s_movk_i32 s2, 42
	s_movk_i32 s46, 43
	v_cmp_gt_u64_e32 vcc, s[2:3], v[246:247]
	v_cmp_gt_u64_e64 s[98:99], s[46:47], v[246:247]
	v_readlane_b32 s3, v247, 19
	v_readlane_b32 s47, v247, 18
	v_addc_co_u32_e32 v52, vcc, 0, v52, vcc
	v_addc_co_u32_e64 v52, s[100:101], 0, v52, s[98:99]
	s_movk_i32 s2, 44
	s_movk_i32 s46, 45
	v_cmp_gt_u64_e32 vcc, s[2:3], v[246:247]
	v_cmp_gt_u64_e64 s[98:99], s[46:47], v[246:247]
	v_readlane_b32 s3, v247, 17
	v_readlane_b32 s47, v247, 16
	v_addc_co_u32_e32 v52, vcc, 0, v52, vcc
	v_addc_co_u32_e64 v52, s[100:101], 0, v52, s[98:99]
	s_movk_i32 s2, 46
	s_movk_i32 s46, 47
	v_cmp_gt_u64_e32 vcc, s[2:3], v[246:247]
	v_cmp_gt_u64_e64 s[98:99], s[46:47], v[246:247]
	v_readlane_b32 s3, v247, 15
	v_readlane_b32 s47, v247, 14
	v_addc_co_u32_e32 v52, vcc, 0, v52, vcc
	v_addc_co_u32_e64 v52, s[100:101], 0, v52, s[98:99]
	s_movk_i32 s2, 48
	s_movk_i32 s46, 49
	v_cmp_gt_u64_e32 vcc, s[2:3], v[246:247]
	v_cmp_gt_u64_e64 s[98:99], s[46:47], v[246:247]
	v_readlane_b32 s3, v247, 13
	v_readlane_b32 s47, v247, 12
	v_addc_co_u32_e32 v52, vcc, 0, v52, vcc
	v_addc_co_u32_e64 v52, s[100:101], 0, v52, s[98:99]
	s_movk_i32 s2, 50
	s_movk_i32 s46, 51
	v_cmp_gt_u64_e32 vcc, s[2:3], v[246:247]
	v_cmp_gt_u64_e64 s[98:99], s[46:47], v[246:247]
	v_readlane_b32 s3, v247, 11
	v_readlane_b32 s47, v247, 10
	v_addc_co_u32_e32 v52, vcc, 0, v52, vcc
	v_addc_co_u32_e64 v52, s[100:101], 0, v52, s[98:99]
	s_movk_i32 s2, 52
	s_movk_i32 s46, 53
	v_cmp_gt_u64_e32 vcc, s[2:3], v[246:247]
	v_cmp_gt_u64_e64 s[98:99], s[46:47], v[246:247]
	v_readlane_b32 s3, v247, 9
	v_readlane_b32 s47, v247, 8
	v_addc_co_u32_e32 v52, vcc, 0, v52, vcc
	v_addc_co_u32_e64 v52, s[100:101], 0, v52, s[98:99]
	s_movk_i32 s2, 54
	s_movk_i32 s46, 55
	v_cmp_gt_u64_e32 vcc, s[2:3], v[246:247]
	v_cmp_gt_u64_e64 s[98:99], s[46:47], v[246:247]
	v_readlane_b32 s3, v247, 7
	v_readlane_b32 s47, v247, 6
	v_addc_co_u32_e32 v52, vcc, 0, v52, vcc
	v_addc_co_u32_e64 v52, s[100:101], 0, v52, s[98:99]
	s_movk_i32 s2, 56
	s_movk_i32 s46, 57
	v_cmp_gt_u64_e32 vcc, s[2:3], v[246:247]
	v_cmp_gt_u64_e64 s[98:99], s[46:47], v[246:247]
	v_readlane_b32 s3, v247, 5
	v_readlane_b32 s47, v247, 4
	v_addc_co_u32_e32 v52, vcc, 0, v52, vcc
	v_addc_co_u32_e64 v52, s[100:101], 0, v52, s[98:99]
	s_movk_i32 s2, 58
	s_movk_i32 s46, 59
	v_cmp_gt_u64_e32 vcc, s[2:3], v[246:247]
	v_cmp_gt_u64_e64 s[98:99], s[46:47], v[246:247]
	v_readlane_b32 s3, v247, 3
	v_readlane_b32 s47, v247, 2
	v_addc_co_u32_e32 v52, vcc, 0, v52, vcc
	v_addc_co_u32_e64 v52, s[100:101], 0, v52, s[98:99]
	s_movk_i32 s2, 60
	s_movk_i32 s46, 61
	v_cmp_gt_u64_e32 vcc, s[2:3], v[246:247]
	v_cmp_gt_u64_e64 s[98:99], s[46:47], v[246:247]
	v_readlane_b32 s3, v247, 1
	v_readlane_b32 s47, v247, 0
	v_addc_co_u32_e32 v52, vcc, 0, v52, vcc
	v_addc_co_u32_e64 v52, s[100:101], 0, v52, s[98:99]
	s_movk_i32 s2, 62
	s_movk_i32 s46, 63
	v_cmp_gt_u64_e32 vcc, s[2:3], v[246:247]
	v_cmp_gt_u64_e64 s[98:99], s[46:47], v[246:247]
	s_nop 1
	v_addc_co_u32_e32 v52, vcc, 0, v52, vcc
	v_addc_co_u32_e64 v52, s[100:101], 0, v52, s[98:99]
	v_cmp_gt_u32_e32 vcc, 16, v52
	s_and_b64 s[2:3], s[42:43], vcc
	v_cndmask_b32_e64 v52, 0, 1, s[2:3]
	v_cmp_ne_u32_e64 s[46:47], 0, v52
	s_and_b64 s[2:3], s[4:5], exec
	s_or_saveexec_b64 s[42:43], s[44:45]
	v_mov_b64_e32 v[52:53], s[46:47]
	s_xor_b64 exec, exec, s[42:43]
	s_cbranch_execnz .LBB0_361
